# resid-epilogue-batched-loads
# speedup vs baseline: 1.0003x; 1.0003x over previous
.LBB0_857:
	v_lshl_add_u32 v172, s76, 8, v33
	v_lshl_or_b32 v173, s27, 8, v161
	v_lshlrev_b32_e32 v164, 2, v186
	v_lshlrev_b32_e32 v163, 2, v187
	v_lshlrev_b32_e32 v154, 12, v172
	v_lshl_add_u32 v154, v173, 1, v154
	v_add_u32_e32 v155, 0x10000, v154
	v_add_u32_e32 v156, 0x20000, v154
	v_add_u32_e32 v157, 0x30000, v154
	v_add_u32_e32 v158, 0x80000, v154
	v_add_u32_e32 v159, 0x90000, v154
	v_add_u32_e32 v168, 0xa0000, v154
	v_add_u32_e32 v169, 0xb0000, v154
	global_load_dwordx4 v[192:195], v154, s[12:13]
	global_load_dwordx4 v[196:199], v154, s[12:13] offset:256
	global_load_dwordx4 v[200:203], v155, s[12:13]
	global_load_dwordx4 v[204:207], v155, s[12:13] offset:256
	global_load_dwordx4 v[208:211], v156, s[12:13]
	global_load_dwordx4 v[212:215], v156, s[12:13] offset:256
	global_load_dwordx4 v[216:219], v157, s[12:13]
	global_load_dwordx4 v[220:223], v157, s[12:13] offset:256
	global_load_dwordx4 v[224:227], v158, s[12:13]
	global_load_dwordx4 v[228:231], v158, s[12:13] offset:256
	global_load_dwordx4 v[232:235], v159, s[12:13]
	global_load_dwordx4 v[236:239], v159, s[12:13] offset:256
	global_load_dwordx4 v[240:243], v168, s[12:13]
	global_load_dwordx4 v[244:247], v168, s[12:13] offset:256
	global_load_dwordx4 v[136:139], v169, s[12:13]
	global_load_dwordx4 v[140:143], v169, s[12:13] offset:256
	s_lshl_b32 s96, s27, 4
	s_lshl_b32 s97, s55, 2
	s_add_i32 s96, s96, s97
	v_lshl_add_u32 v177, v172, 7, s96
	s_waitcnt vmcnt(15)
	v_lshlrev_b32_e32 v172, 16, v192
	v_and_b32_e32 v173, 0xffff0000, v192
	v_lshlrev_b32_e32 v174, 16, v193
	v_and_b32_e32 v175, 0xffff0000, v193
	v_lshlrev_b32_e32 v192, 16, v194
	v_and_b32_e32 v193, 0xffff0000, v194
	v_lshlrev_b32_e32 v194, 16, v195
	v_and_b32_e32 v195, 0xffff0000, v195
	v_pk_add_f32 v[132:133], v[132:133], v[172:173]
	v_pk_add_f32 v[134:135], v[134:135], v[174:175]
	v_pk_add_f32 v[128:129], v[128:129], v[192:193]
	v_pk_add_f32 v[130:131], v[130:131], v[194:195]
	v_cvt_pk_bf16_f32 v172, v132, v133
	v_cvt_pk_bf16_f32 v173, v134, v135
	v_cvt_pk_bf16_f32 v174, v128, v129
	v_cvt_pk_bf16_f32 v175, v130, v131
	global_store_dwordx4 v154, v[172:175], s[12:13]
	v_mul_f32_e32 v192, v133, v133
	v_mul_f32_e32 v193, v135, v135
	v_fmac_f32_e32 v192, v132, v132
	v_fmac_f32_e32 v193, v134, v134
	v_add_f32_e32 v192, v192, v193
	v_mul_f32_e32 v193, v129, v129
	v_mul_f32_e32 v194, v131, v131
	v_fmac_f32_e32 v193, v128, v128
	v_fmac_f32_e32 v194, v130, v130
	v_add_f32_e32 v193, v193, v194
	v_add_f32_e32 v176, v192, v193
	s_waitcnt vmcnt(15)
	v_lshlrev_b32_e32 v128, 16, v196
	v_and_b32_e32 v129, 0xffff0000, v196
	v_lshlrev_b32_e32 v130, 16, v197
	v_and_b32_e32 v131, 0xffff0000, v197
	v_lshlrev_b32_e32 v196, 16, v198
	v_and_b32_e32 v197, 0xffff0000, v198
	v_lshlrev_b32_e32 v198, 16, v199
	v_and_b32_e32 v199, 0xffff0000, v199
	v_pk_add_f32 v[124:125], v[124:125], v[128:129]
	v_pk_add_f32 v[126:127], v[126:127], v[130:131]
	v_pk_add_f32 v[120:121], v[120:121], v[196:197]
	v_pk_add_f32 v[122:123], v[122:123], v[198:199]
	v_cvt_pk_bf16_f32 v128, v124, v125
	v_cvt_pk_bf16_f32 v129, v126, v127
	v_cvt_pk_bf16_f32 v130, v120, v121
	v_cvt_pk_bf16_f32 v131, v122, v123
	global_store_dwordx4 v154, v[128:131], s[12:13] offset:256
	v_mul_f32_e32 v196, v125, v125
	v_mul_f32_e32 v197, v127, v127
	v_fmac_f32_e32 v196, v124, v124
	v_fmac_f32_e32 v197, v126, v126
	v_add_f32_e32 v196, v196, v197
	v_mul_f32_e32 v197, v121, v121
	v_mul_f32_e32 v198, v123, v123
	v_fmac_f32_e32 v197, v120, v120
	v_fmac_f32_e32 v198, v122, v122
	v_add_f32_e32 v197, v197, v198
	v_add_f32_e32 v196, v196, v197
	v_add_f32_e32 v124, v176, v196
	s_waitcnt vmcnt(15)
	v_lshlrev_b32_e32 v120, 16, v200
	v_and_b32_e32 v121, 0xffff0000, v200
	v_lshlrev_b32_e32 v122, 16, v201
	v_and_b32_e32 v123, 0xffff0000, v201
	v_lshlrev_b32_e32 v200, 16, v202
	v_and_b32_e32 v201, 0xffff0000, v202
	v_lshlrev_b32_e32 v202, 16, v203
	v_and_b32_e32 v203, 0xffff0000, v203
	v_pk_add_f32 v[116:117], v[116:117], v[120:121]
	v_pk_add_f32 v[118:119], v[118:119], v[122:123]
	v_pk_add_f32 v[112:113], v[112:113], v[200:201]
	v_pk_add_f32 v[114:115], v[114:115], v[202:203]
	v_cvt_pk_bf16_f32 v120, v116, v117
	v_cvt_pk_bf16_f32 v121, v118, v119
	v_cvt_pk_bf16_f32 v122, v112, v113
	v_cvt_pk_bf16_f32 v123, v114, v115
	global_store_dwordx4 v155, v[120:123], s[12:13]
	v_mul_f32_e32 v200, v117, v117
	v_mul_f32_e32 v201, v119, v119
	v_fmac_f32_e32 v200, v116, v116
	v_fmac_f32_e32 v201, v118, v118
	v_add_f32_e32 v200, v200, v201
	v_mul_f32_e32 v201, v113, v113
	v_mul_f32_e32 v202, v115, v115
	v_fmac_f32_e32 v201, v112, v112
	v_fmac_f32_e32 v202, v114, v114
	v_add_f32_e32 v201, v201, v202
	v_add_f32_e32 v176, v200, v201
	s_waitcnt vmcnt(15)
	v_lshlrev_b32_e32 v112, 16, v204
	v_and_b32_e32 v113, 0xffff0000, v204
	v_lshlrev_b32_e32 v114, 16, v205
	v_and_b32_e32 v115, 0xffff0000, v205
	v_lshlrev_b32_e32 v204, 16, v206
	v_and_b32_e32 v205, 0xffff0000, v206
	v_lshlrev_b32_e32 v206, 16, v207
	v_and_b32_e32 v207, 0xffff0000, v207
	v_pk_add_f32 v[108:109], v[108:109], v[112:113]
	v_pk_add_f32 v[110:111], v[110:111], v[114:115]
	v_pk_add_f32 v[104:105], v[104:105], v[204:205]
	v_pk_add_f32 v[106:107], v[106:107], v[206:207]
	v_cvt_pk_bf16_f32 v112, v108, v109
	v_cvt_pk_bf16_f32 v113, v110, v111
	v_cvt_pk_bf16_f32 v114, v104, v105
	v_cvt_pk_bf16_f32 v115, v106, v107
	global_store_dwordx4 v155, v[112:115], s[12:13] offset:256
	v_mul_f32_e32 v204, v109, v109
	v_mul_f32_e32 v205, v111, v111
	v_fmac_f32_e32 v204, v108, v108
	v_fmac_f32_e32 v205, v110, v110
	v_add_f32_e32 v204, v204, v205
	v_mul_f32_e32 v205, v105, v105
	v_mul_f32_e32 v206, v107, v107
	v_fmac_f32_e32 v205, v104, v104
	v_fmac_f32_e32 v206, v106, v106
	v_add_f32_e32 v205, v205, v206
	v_add_f32_e32 v204, v204, v205
	v_add_f32_e32 v108, v176, v204
	s_waitcnt vmcnt(15)
	v_lshlrev_b32_e32 v104, 16, v208
	v_and_b32_e32 v105, 0xffff0000, v208
	v_lshlrev_b32_e32 v106, 16, v209
	v_and_b32_e32 v107, 0xffff0000, v209
	v_lshlrev_b32_e32 v208, 16, v210
	v_and_b32_e32 v209, 0xffff0000, v210
	v_lshlrev_b32_e32 v210, 16, v211
	v_and_b32_e32 v211, 0xffff0000, v211
	v_pk_add_f32 v[100:101], v[100:101], v[104:105]
	v_pk_add_f32 v[102:103], v[102:103], v[106:107]
	v_pk_add_f32 v[96:97], v[96:97], v[208:209]
	v_pk_add_f32 v[98:99], v[98:99], v[210:211]
	v_cvt_pk_bf16_f32 v104, v100, v101
	v_cvt_pk_bf16_f32 v105, v102, v103
	v_cvt_pk_bf16_f32 v106, v96, v97
	v_cvt_pk_bf16_f32 v107, v98, v99
	global_store_dwordx4 v156, v[104:107], s[12:13]
	v_mul_f32_e32 v208, v101, v101
	v_mul_f32_e32 v209, v103, v103
	v_fmac_f32_e32 v208, v100, v100
	v_fmac_f32_e32 v209, v102, v102
	v_add_f32_e32 v208, v208, v209
	v_mul_f32_e32 v209, v97, v97
	v_mul_f32_e32 v210, v99, v99
	v_fmac_f32_e32 v209, v96, v96
	v_fmac_f32_e32 v210, v98, v98
	v_add_f32_e32 v209, v209, v210
	v_add_f32_e32 v176, v208, v209
	s_waitcnt vmcnt(15)
	v_lshlrev_b32_e32 v96, 16, v212
	v_and_b32_e32 v97, 0xffff0000, v212
	v_lshlrev_b32_e32 v98, 16, v213
	v_and_b32_e32 v99, 0xffff0000, v213
	v_lshlrev_b32_e32 v212, 16, v214
	v_and_b32_e32 v213, 0xffff0000, v214
	v_lshlrev_b32_e32 v214, 16, v215
	v_and_b32_e32 v215, 0xffff0000, v215
	v_pk_add_f32 v[92:93], v[92:93], v[96:97]
	v_pk_add_f32 v[94:95], v[94:95], v[98:99]
	v_pk_add_f32 v[88:89], v[88:89], v[212:213]
	v_pk_add_f32 v[90:91], v[90:91], v[214:215]
	v_cvt_pk_bf16_f32 v96, v92, v93
	v_cvt_pk_bf16_f32 v97, v94, v95
	v_cvt_pk_bf16_f32 v98, v88, v89
	v_cvt_pk_bf16_f32 v99, v90, v91
	global_store_dwordx4 v156, v[96:99], s[12:13] offset:256
	v_mul_f32_e32 v212, v93, v93
	v_mul_f32_e32 v213, v95, v95
	v_fmac_f32_e32 v212, v92, v92
	v_fmac_f32_e32 v213, v94, v94
	v_add_f32_e32 v212, v212, v213
	v_mul_f32_e32 v213, v89, v89
	v_mul_f32_e32 v214, v91, v91
	v_fmac_f32_e32 v213, v88, v88
	v_fmac_f32_e32 v214, v90, v90
	v_add_f32_e32 v213, v213, v214
	v_add_f32_e32 v212, v212, v213
	v_add_f32_e32 v92, v176, v212
	s_waitcnt vmcnt(15)
	v_lshlrev_b32_e32 v88, 16, v216
	v_and_b32_e32 v89, 0xffff0000, v216
	v_lshlrev_b32_e32 v90, 16, v217
	v_and_b32_e32 v91, 0xffff0000, v217
	v_lshlrev_b32_e32 v216, 16, v218
	v_and_b32_e32 v217, 0xffff0000, v218
	v_lshlrev_b32_e32 v218, 16, v219
	v_and_b32_e32 v219, 0xffff0000, v219
	v_pk_add_f32 v[84:85], v[84:85], v[88:89]
	v_pk_add_f32 v[86:87], v[86:87], v[90:91]
	v_pk_add_f32 v[80:81], v[80:81], v[216:217]
	v_pk_add_f32 v[82:83], v[82:83], v[218:219]
	v_cvt_pk_bf16_f32 v88, v84, v85
	v_cvt_pk_bf16_f32 v89, v86, v87
	v_cvt_pk_bf16_f32 v90, v80, v81
	v_cvt_pk_bf16_f32 v91, v82, v83
	global_store_dwordx4 v157, v[88:91], s[12:13]
	v_mul_f32_e32 v216, v85, v85
	v_mul_f32_e32 v217, v87, v87
	v_fmac_f32_e32 v216, v84, v84
	v_fmac_f32_e32 v217, v86, v86
	v_add_f32_e32 v216, v216, v217
	v_mul_f32_e32 v217, v81, v81
	v_mul_f32_e32 v218, v83, v83
	v_fmac_f32_e32 v217, v80, v80
	v_fmac_f32_e32 v218, v82, v82
	v_add_f32_e32 v217, v217, v218
	v_add_f32_e32 v176, v216, v217
	s_waitcnt vmcnt(15)
	v_lshlrev_b32_e32 v80, 16, v220
	v_and_b32_e32 v81, 0xffff0000, v220
	v_lshlrev_b32_e32 v82, 16, v221
	v_and_b32_e32 v83, 0xffff0000, v221
	v_lshlrev_b32_e32 v220, 16, v222
	v_and_b32_e32 v221, 0xffff0000, v222
	v_lshlrev_b32_e32 v222, 16, v223
	v_and_b32_e32 v223, 0xffff0000, v223
	v_pk_add_f32 v[76:77], v[76:77], v[80:81]
	v_pk_add_f32 v[78:79], v[78:79], v[82:83]
	v_pk_add_f32 v[72:73], v[72:73], v[220:221]
	v_pk_add_f32 v[74:75], v[74:75], v[222:223]
	v_cvt_pk_bf16_f32 v80, v76, v77
	v_cvt_pk_bf16_f32 v81, v78, v79
	v_cvt_pk_bf16_f32 v82, v72, v73
	v_cvt_pk_bf16_f32 v83, v74, v75
	global_store_dwordx4 v157, v[80:83], s[12:13] offset:256
	v_mul_f32_e32 v220, v77, v77
	v_mul_f32_e32 v221, v79, v79
	v_fmac_f32_e32 v220, v76, v76
	v_fmac_f32_e32 v221, v78, v78
	v_add_f32_e32 v220, v220, v221
	v_mul_f32_e32 v221, v73, v73
	v_mul_f32_e32 v222, v75, v75
	v_fmac_f32_e32 v221, v72, v72
	v_fmac_f32_e32 v222, v74, v74
	v_add_f32_e32 v221, v221, v222
	v_add_f32_e32 v220, v220, v221
	v_add_f32_e32 v76, v176, v220
	s_waitcnt vmcnt(15)
	v_lshlrev_b32_e32 v72, 16, v224
	v_and_b32_e32 v73, 0xffff0000, v224
	v_lshlrev_b32_e32 v74, 16, v225
	v_and_b32_e32 v75, 0xffff0000, v225
	v_lshlrev_b32_e32 v224, 16, v226
	v_and_b32_e32 v225, 0xffff0000, v226
	v_lshlrev_b32_e32 v226, 16, v227
	v_and_b32_e32 v227, 0xffff0000, v227
	v_pk_add_f32 v[68:69], v[68:69], v[72:73]
	v_pk_add_f32 v[70:71], v[70:71], v[74:75]
	v_pk_add_f32 v[64:65], v[64:65], v[224:225]
	v_pk_add_f32 v[66:67], v[66:67], v[226:227]
	v_cvt_pk_bf16_f32 v72, v68, v69
	v_cvt_pk_bf16_f32 v73, v70, v71
	v_cvt_pk_bf16_f32 v74, v64, v65
	v_cvt_pk_bf16_f32 v75, v66, v67
	global_store_dwordx4 v158, v[72:75], s[12:13]
	v_mul_f32_e32 v224, v69, v69
	v_mul_f32_e32 v225, v71, v71
	v_fmac_f32_e32 v224, v68, v68
	v_fmac_f32_e32 v225, v70, v70
	v_add_f32_e32 v224, v224, v225
	v_mul_f32_e32 v225, v65, v65
	v_mul_f32_e32 v226, v67, v67
	v_fmac_f32_e32 v225, v64, v64
	v_fmac_f32_e32 v226, v66, v66
	v_add_f32_e32 v225, v225, v226
	v_add_f32_e32 v176, v224, v225
	s_waitcnt vmcnt(15)
	v_lshlrev_b32_e32 v64, 16, v228
	v_and_b32_e32 v65, 0xffff0000, v228
	v_lshlrev_b32_e32 v66, 16, v229
	v_and_b32_e32 v67, 0xffff0000, v229
	v_lshlrev_b32_e32 v228, 16, v230
	v_and_b32_e32 v229, 0xffff0000, v230
	v_lshlrev_b32_e32 v230, 16, v231
	v_and_b32_e32 v231, 0xffff0000, v231
	v_pk_add_f32 v[60:61], v[60:61], v[64:65]
	v_pk_add_f32 v[62:63], v[62:63], v[66:67]
	v_pk_add_f32 v[56:57], v[56:57], v[228:229]
	v_pk_add_f32 v[58:59], v[58:59], v[230:231]
	v_cvt_pk_bf16_f32 v64, v60, v61
	v_cvt_pk_bf16_f32 v65, v62, v63
	v_cvt_pk_bf16_f32 v66, v56, v57
	v_cvt_pk_bf16_f32 v67, v58, v59
	global_store_dwordx4 v158, v[64:67], s[12:13] offset:256
	v_mul_f32_e32 v228, v61, v61
	v_mul_f32_e32 v229, v63, v63
	v_fmac_f32_e32 v228, v60, v60
	v_fmac_f32_e32 v229, v62, v62
	v_add_f32_e32 v228, v228, v229
	v_mul_f32_e32 v229, v57, v57
	v_mul_f32_e32 v230, v59, v59
	v_fmac_f32_e32 v229, v56, v56
	v_fmac_f32_e32 v230, v58, v58
	v_add_f32_e32 v229, v229, v230
	v_add_f32_e32 v228, v228, v229
	v_add_f32_e32 v60, v176, v228
	s_waitcnt vmcnt(15)
	v_lshlrev_b32_e32 v56, 16, v232
	v_and_b32_e32 v57, 0xffff0000, v232
	v_lshlrev_b32_e32 v58, 16, v233
	v_and_b32_e32 v59, 0xffff0000, v233
	v_lshlrev_b32_e32 v232, 16, v234
	v_and_b32_e32 v233, 0xffff0000, v234
	v_lshlrev_b32_e32 v234, 16, v235
	v_and_b32_e32 v235, 0xffff0000, v235
	v_pk_add_f32 v[52:53], v[52:53], v[56:57]
	v_pk_add_f32 v[54:55], v[54:55], v[58:59]
	v_pk_add_f32 v[48:49], v[48:49], v[232:233]
	v_pk_add_f32 v[50:51], v[50:51], v[234:235]
	v_cvt_pk_bf16_f32 v56, v52, v53
	v_cvt_pk_bf16_f32 v57, v54, v55
	v_cvt_pk_bf16_f32 v58, v48, v49
	v_cvt_pk_bf16_f32 v59, v50, v51
	global_store_dwordx4 v159, v[56:59], s[12:13]
	v_mul_f32_e32 v232, v53, v53
	v_mul_f32_e32 v233, v55, v55
	v_fmac_f32_e32 v232, v52, v52
	v_fmac_f32_e32 v233, v54, v54
	v_add_f32_e32 v232, v232, v233
	v_mul_f32_e32 v233, v49, v49
	v_mul_f32_e32 v234, v51, v51
	v_fmac_f32_e32 v233, v48, v48
	v_fmac_f32_e32 v234, v50, v50
	v_add_f32_e32 v233, v233, v234
	v_add_f32_e32 v176, v232, v233
	s_waitcnt vmcnt(15)
	v_lshlrev_b32_e32 v48, 16, v236
	v_and_b32_e32 v49, 0xffff0000, v236
	v_lshlrev_b32_e32 v50, 16, v237
	v_and_b32_e32 v51, 0xffff0000, v237
	v_lshlrev_b32_e32 v236, 16, v238
	v_and_b32_e32 v237, 0xffff0000, v238
	v_lshlrev_b32_e32 v238, 16, v239
	v_and_b32_e32 v239, 0xffff0000, v239
	v_pk_add_f32 v[44:45], v[44:45], v[48:49]
	v_pk_add_f32 v[46:47], v[46:47], v[50:51]
	v_pk_add_f32 v[40:41], v[40:41], v[236:237]
	v_pk_add_f32 v[42:43], v[42:43], v[238:239]
	v_cvt_pk_bf16_f32 v48, v44, v45
	v_cvt_pk_bf16_f32 v49, v46, v47
	v_cvt_pk_bf16_f32 v50, v40, v41
	v_cvt_pk_bf16_f32 v51, v42, v43
	global_store_dwordx4 v159, v[48:51], s[12:13] offset:256
	v_mul_f32_e32 v236, v45, v45
	v_mul_f32_e32 v237, v47, v47
	v_fmac_f32_e32 v236, v44, v44
	v_fmac_f32_e32 v237, v46, v46
	v_add_f32_e32 v236, v236, v237
	v_mul_f32_e32 v237, v41, v41
	v_mul_f32_e32 v238, v43, v43
	v_fmac_f32_e32 v237, v40, v40
	v_fmac_f32_e32 v238, v42, v42
	v_add_f32_e32 v237, v237, v238
	v_add_f32_e32 v236, v236, v237
	v_add_f32_e32 v44, v176, v236
	s_waitcnt vmcnt(15)
	v_lshlrev_b32_e32 v40, 16, v240
	v_and_b32_e32 v41, 0xffff0000, v240
	v_lshlrev_b32_e32 v42, 16, v241
	v_and_b32_e32 v43, 0xffff0000, v241
	v_lshlrev_b32_e32 v240, 16, v242
	v_and_b32_e32 v241, 0xffff0000, v242
	v_lshlrev_b32_e32 v242, 16, v243
	v_and_b32_e32 v243, 0xffff0000, v243
	v_pk_add_f32 v[28:29], v[28:29], v[40:41]
	v_pk_add_f32 v[30:31], v[30:31], v[42:43]
	v_pk_add_f32 v[24:25], v[24:25], v[240:241]
	v_pk_add_f32 v[26:27], v[26:27], v[242:243]
	v_cvt_pk_bf16_f32 v40, v28, v29
	v_cvt_pk_bf16_f32 v41, v30, v31
	v_cvt_pk_bf16_f32 v42, v24, v25
	v_cvt_pk_bf16_f32 v43, v26, v27
	global_store_dwordx4 v168, v[40:43], s[12:13]
	v_mul_f32_e32 v240, v29, v29
	v_mul_f32_e32 v241, v31, v31
	v_fmac_f32_e32 v240, v28, v28
	v_fmac_f32_e32 v241, v30, v30
	v_add_f32_e32 v240, v240, v241
	v_mul_f32_e32 v241, v25, v25
	v_mul_f32_e32 v242, v27, v27
	v_fmac_f32_e32 v241, v24, v24
	v_fmac_f32_e32 v242, v26, v26
	v_add_f32_e32 v241, v241, v242
	v_add_f32_e32 v176, v240, v241
	s_waitcnt vmcnt(15)
	v_lshlrev_b32_e32 v24, 16, v244
	v_and_b32_e32 v25, 0xffff0000, v244
	v_lshlrev_b32_e32 v26, 16, v245
	v_and_b32_e32 v27, 0xffff0000, v245
	v_lshlrev_b32_e32 v244, 16, v246
	v_and_b32_e32 v245, 0xffff0000, v246
	v_lshlrev_b32_e32 v246, 16, v247
	v_and_b32_e32 v247, 0xffff0000, v247
	v_pk_add_f32 v[20:21], v[20:21], v[24:25]
	v_pk_add_f32 v[22:23], v[22:23], v[26:27]
	v_pk_add_f32 v[16:17], v[16:17], v[244:245]
	v_pk_add_f32 v[18:19], v[18:19], v[246:247]
	v_cvt_pk_bf16_f32 v24, v20, v21
	v_cvt_pk_bf16_f32 v25, v22, v23
	v_cvt_pk_bf16_f32 v26, v16, v17
	v_cvt_pk_bf16_f32 v27, v18, v19
	global_store_dwordx4 v168, v[24:27], s[12:13] offset:256
	v_mul_f32_e32 v244, v21, v21
	v_mul_f32_e32 v245, v23, v23
	v_fmac_f32_e32 v244, v20, v20
	v_fmac_f32_e32 v245, v22, v22
	v_add_f32_e32 v244, v244, v245
	v_mul_f32_e32 v245, v17, v17
	v_mul_f32_e32 v246, v19, v19
	v_fmac_f32_e32 v245, v16, v16
	v_fmac_f32_e32 v246, v18, v18
	v_add_f32_e32 v245, v245, v246
	v_add_f32_e32 v244, v244, v245
	v_add_f32_e32 v20, v176, v244
	s_waitcnt vmcnt(15)
	v_lshlrev_b32_e32 v16, 16, v136
	v_and_b32_e32 v17, 0xffff0000, v136
	v_lshlrev_b32_e32 v18, 16, v137
	v_and_b32_e32 v19, 0xffff0000, v137
	v_lshlrev_b32_e32 v136, 16, v138
	v_and_b32_e32 v137, 0xffff0000, v138
	v_lshlrev_b32_e32 v138, 16, v139
	v_and_b32_e32 v139, 0xffff0000, v139
	v_pk_add_f32 v[12:13], v[12:13], v[16:17]
	v_pk_add_f32 v[14:15], v[14:15], v[18:19]
	v_pk_add_f32 v[8:9], v[8:9], v[136:137]
	v_pk_add_f32 v[10:11], v[10:11], v[138:139]
	v_cvt_pk_bf16_f32 v16, v12, v13
	v_cvt_pk_bf16_f32 v17, v14, v15
	v_cvt_pk_bf16_f32 v18, v8, v9
	v_cvt_pk_bf16_f32 v19, v10, v11
	global_store_dwordx4 v169, v[16:19], s[12:13]
	v_mul_f32_e32 v136, v13, v13
	v_mul_f32_e32 v137, v15, v15
	v_fmac_f32_e32 v136, v12, v12
	v_fmac_f32_e32 v137, v14, v14
	v_add_f32_e32 v136, v136, v137
	v_mul_f32_e32 v137, v9, v9
	v_mul_f32_e32 v138, v11, v11
	v_fmac_f32_e32 v137, v8, v8
	v_fmac_f32_e32 v138, v10, v10
	v_add_f32_e32 v137, v137, v138
	v_add_f32_e32 v176, v136, v137
	s_waitcnt vmcnt(15)
	v_lshlrev_b32_e32 v8, 16, v140
	v_and_b32_e32 v9, 0xffff0000, v140
	v_lshlrev_b32_e32 v10, 16, v141
	v_and_b32_e32 v11, 0xffff0000, v141
	v_lshlrev_b32_e32 v140, 16, v142
	v_and_b32_e32 v141, 0xffff0000, v142
	v_lshlrev_b32_e32 v142, 16, v143
	v_and_b32_e32 v143, 0xffff0000, v143
	v_pk_add_f32 v[4:5], v[4:5], v[8:9]
	v_pk_add_f32 v[6:7], v[6:7], v[10:11]
	v_pk_add_f32 v[0:1], v[0:1], v[140:141]
	v_pk_add_f32 v[2:3], v[2:3], v[142:143]
	v_cvt_pk_bf16_f32 v8, v4, v5
	v_cvt_pk_bf16_f32 v9, v6, v7
	v_cvt_pk_bf16_f32 v10, v0, v1
	v_cvt_pk_bf16_f32 v11, v2, v3
	global_store_dwordx4 v169, v[8:11], s[12:13] offset:256
	v_mul_f32_e32 v140, v5, v5
	v_mul_f32_e32 v141, v7, v7
	v_fmac_f32_e32 v140, v4, v4
	v_fmac_f32_e32 v141, v6, v6
	v_add_f32_e32 v140, v140, v141
	v_mul_f32_e32 v141, v1, v1
	v_mul_f32_e32 v142, v3, v3
	v_fmac_f32_e32 v141, v0, v0
	v_fmac_f32_e32 v142, v2, v2
	v_add_f32_e32 v141, v141, v142
	v_add_f32_e32 v140, v140, v141
	v_add_f32_e32 v4, v176, v140
	ds_bpermute_b32 v125, v164, v124
	ds_bpermute_b32 v109, v164, v108
	ds_bpermute_b32 v93, v164, v92
	ds_bpermute_b32 v77, v164, v76
	ds_bpermute_b32 v61, v164, v60
	ds_bpermute_b32 v45, v164, v44
	ds_bpermute_b32 v21, v164, v20
	ds_bpermute_b32 v5, v164, v4
	s_waitcnt lgkmcnt(0)
	v_add_f32_e32 v124, v124, v125
	v_add_f32_e32 v108, v108, v109
	v_add_f32_e32 v92, v92, v93
	v_add_f32_e32 v76, v76, v77
	v_add_f32_e32 v60, v60, v61
	v_add_f32_e32 v44, v44, v45
	v_add_f32_e32 v20, v20, v21
	v_add_f32_e32 v4, v4, v5
	ds_bpermute_b32 v125, v163, v124
	ds_bpermute_b32 v109, v163, v108
	ds_bpermute_b32 v93, v163, v92
	ds_bpermute_b32 v77, v163, v76
	ds_bpermute_b32 v61, v163, v60
	ds_bpermute_b32 v45, v163, v44
	ds_bpermute_b32 v21, v163, v20
	ds_bpermute_b32 v5, v163, v4
	v_add_u32_e32 v192, 0x1000, v177
	v_add_u32_e32 v193, 0x4000, v177
	v_add_u32_e32 v194, 0x5000, v177
	s_waitcnt lgkmcnt(0)
	s_and_saveexec_b64 s[24:25], s[36:37]
	s_cbranch_execz .LBB0_873
	v_add_f32_e32 v124, v124, v125
	v_add_f32_e32 v108, v108, v109
	v_add_f32_e32 v92, v92, v93
	v_add_f32_e32 v76, v76, v77
	v_add_f32_e32 v60, v60, v61
	v_add_f32_e32 v44, v44, v45
	v_add_f32_e32 v20, v20, v21
	v_add_f32_e32 v4, v4, v5
	global_store_dword v177, v124, s[42:43]
	global_store_dword v177, v108, s[42:43] offset:2048
	global_store_dword v192, v92, s[42:43]
	global_store_dword v192, v76, s[42:43] offset:2048
	global_store_dword v193, v60, s[42:43]
	global_store_dword v193, v44, s[42:43] offset:2048
	global_store_dword v194, v20, s[42:43]
	global_store_dword v194, v4, s[42:43] offset:2048
